# conversion item order: adjacent waves take the two 64-row k blocks of the same column block (256 contiguous bytes per output row written by a wave pair)
# speedup vs baseline: 1.0049x; 1.0049x over previous
; DI void phase_prologue(const Frame& F0, const Args& a) {
;     ...
;         for (int it = gw; it < NITEMS; it += NGW) {
;             int r = it;
;             if (r < 2 * I_IN) { const int j = r / I_IN; r %= I_IN; const int nblk = GIN / 32, kb = r / nblk, nb = r % nblk;
;                 transpose_item(a.gla_w_in + (size_t)j * DM * GIN, DM, GIN, (bf16*)(ws + WS_WIN) + (size_t)j * GIN_PAD * DM, 64 * kb, 32 * nb, 32 * nb, scr, F.lane); continue; }
;             r -= 2 * I_IN;
;             if (r < 2 * I_SQ) { const int j = r / I_SQ; r %= I_SQ; const int kb = r / 64, nb = r % 64;
;                 transpose_item(a.gla_w_out + (size_t)j * DM * DM, DM, DM, (bf16*)(ws + WS_WGO) + (size_t)j * DM * DM, 64 * kb, 32 * nb, 32 * nb, scr, F.lane); continue; }
;             r -= 2 * I_SQ;
;             if (r < 2 * I_SQ) { const int j = r / I_SQ; r %= I_SQ; const int kb = r / 64, nb = r % 64;
;                 transpose_item(a.fnet_w_out + (size_t)j * DM * DM, DM, DM, (bf16*)(ws + WS_WFO) + (size_t)j * DM * DM, 64 * kb, 32 * nb, 32 * nb, scr, F.lane, 1); continue; }
;             r -= 2 * I_SQ;
;             if (r < DEPTH * I_GU) { const int j = r / I_GU; r %= I_GU; const int nblk = 2 * DFF / 32, kb = r / nblk, nb = r % nblk, n0 = 32 * nb;
;                 const int jj = n0 < DFF ? n0 : n0 - DFF; const int drow = (jj >> 7) * 256 + (n0 < DFF ? 0 : 128) + (jj & 127);
;                 transpose_item(a.ffn_w_gu + (size_t)j * DM * 2 * DFF, DM, 2 * DFF, (bf16*)(ws + WS_WGU) + (size_t)j * 2 * DFF * DM, 64 * kb, n0, drow, scr, F.lane); continue; }
;             r -= DEPTH * I_GU;
;             { const int j = r / I_DN; r %= I_DN; const int kb = r / 64, nb = r % 64;
;                 transpose_item(a.ffn_w_down + (size_t)j * DFF * DM, DFF, DM, (bf16*)(ws + WS_WDN) + (size_t)j * DM * DFF, 64 * kb, 32 * nb, 32 * nb, scr, F.lane); }
.Lcv_t_dn:
	s_sub_u32 s0, s6, 0x10040
	s_mul_hi_u32 s7, s0, 0xba2e9
	s_mul_i32 s1, s7, 0x1600
	s_sub_u32 s0, s0, s1
	s_and_b32 s16, s0, 1
	s_lshr_b32 s0, s0, 1
	s_lshr_b32 s8, s0, 6
	s_mul_i32 s1, s8, 0x40
	s_sub_u32 s9, s0, s1
	s_lshl_b32 s8, s8, 1
	s_or_b32 s8, s8, s16
	s_mov_b32 s10, 0x1600
	s_mov_b32 s16, 0x2000
	s_mov_b32 s11, 0x800
	s_mov_b32 s30, 0x2c00
	s_mov_b32 s17, 0
	s_mov_b32 s14, 0x102a0000
	s_lshl_b32 s15, s9, 5
	v_readlane_b32 s4, v252, 0
	v_readlane_b32 s5, v252, 1
	s_branch .Lcv_tcommon
.Lcv_t_gu:
	s_sub_u32 s0, s6, 0x5040
	s_mul_hi_u32 s7, s0, 0x5d175
	s_mul_i32 s1, s7, 0x2c00
	s_sub_u32 s0, s0, s1
	s_and_b32 s16, s0, 1
	s_lshr_b32 s0, s0, 1
	s_mul_hi_u32 s8, s0, 0xba2e8c
	s_mul_i32 s1, s8, 0x160
	s_sub_u32 s9, s0, s1
	s_lshl_b32 s8, s8, 1
	s_or_b32 s8, s8, s16
	s_mov_b32 s10, 0x800
	s_mov_b32 s16, 0xb000
	s_mov_b32 s11, 0x2c00
	s_mov_b32 s30, 0x1000
	s_mov_b32 s17, 0
	s_mov_b32 s14, 0x52a0000
	s_lshl_b32 s15, s9, 5
	s_cmp_lt_u32 s15, 0x1600
	s_cselect_b32 s0, 0, 0x1600
	s_cselect_b32 s1, 0, 0x80
	s_sub_u32 s15, s15, s0
	s_lshr_b32 s0, s15, 7
	s_lshl_b32 s0, s0, 8
	s_and_b32 s15, s15, 0x7f
	s_add_u32 s15, s15, s0
	s_add_u32 s15, s15, s1
	v_readlane_b32 s4, v252, 38
	v_readlane_b32 s5, v252, 39
	s_branch .Lcv_tcommon
.Lcv_t_fo:
	s_sub_u32 s0, s6, 0x4040
	s_lshr_b32 s7, s0, 11
	s_mul_i32 s1, s7, 0x800
	s_sub_u32 s0, s0, s1
	s_and_b32 s16, s0, 1
	s_lshr_b32 s0, s0, 1
	s_lshr_b32 s8, s0, 6
	s_mul_i32 s1, s8, 0x40
	s_sub_u32 s9, s0, s1
	s_lshl_b32 s8, s8, 1
	s_or_b32 s8, s8, s16
	s_mov_b32 s10, 0x800
	s_mov_b32 s16, 0x2000
	s_mov_b32 s11, 0x800
	s_mov_b32 s30, 0x1000
	s_mov_b32 s17, 1
	s_mov_b32 s14, 0x42a0000
	s_lshl_b32 s15, s9, 5
	v_readlane_b32 s4, v252, 36
	v_readlane_b32 s5, v252, 37
	s_branch .Lcv_tcommon
.Lcv_t_go:
	s_sub_u32 s0, s6, 0x3040
	s_lshr_b32 s7, s0, 11
	s_mul_i32 s1, s7, 0x800
	s_sub_u32 s0, s0, s1
	s_and_b32 s16, s0, 1
	s_lshr_b32 s0, s0, 1
	s_lshr_b32 s8, s0, 6
	s_mul_i32 s1, s8, 0x40
	s_sub_u32 s9, s0, s1
	s_lshl_b32 s8, s8, 1
	s_or_b32 s8, s8, s16
	s_mov_b32 s10, 0x800
	s_mov_b32 s16, 0x2000
	s_mov_b32 s11, 0x800
	s_mov_b32 s30, 0x1000
	s_mov_b32 s17, 0
	s_mov_b32 s14, 0x32a0000
	s_lshl_b32 s15, s9, 5
	v_readlane_b32 s4, v252, 34
	v_readlane_b32 s5, v252, 35
	s_branch .Lcv_tcommon
.Lcv_t_win:
	s_mov_b32 s0, s6
	s_mul_hi_u32 s7, s0, 0xa9c85
	s_mul_i32 s1, s7, 0x1820
	s_sub_u32 s0, s0, s1
	s_and_b32 s16, s0, 1
	s_lshr_b32 s0, s0, 1
	s_mul_hi_u32 s8, s0, 0x1539095
	s_mul_i32 s1, s8, 0xc1
	s_sub_u32 s9, s0, s1
	s_lshl_b32 s8, s8, 1
	s_or_b32 s8, s8, s16
	s_mov_b32 s10, 0x800
	s_mov_b32 s16, 0x6080
	s_mov_b32 s11, 0x1900
	s_mov_b32 s30, 0x1000
	s_mov_b32 s17, 0
	s_mov_b32 s14, 0xa0000
	s_lshl_b32 s15, s9, 5
	v_readlane_b32 s4, v252, 22
	v_readlane_b32 s5, v252, 23
	s_branch .Lcv_tcommon
